# P0 work split refined: waves owning a mods GEMV item also take one weight-transpose item each, other waves take the rest (stride 896); on top of EpiDil/P0/P3 changes
# speedup vs baseline: 1.0045x; 1.0016x over previous
; __global__ void __launch_bounds__(512, 2) fwd_megakernel(Args a_by_value) {
;     ...
;     if (ON(0)) for (int it = gw; it < 72 * 16; it += NGW) mods_item(a, mods, scr, it, lane);
;     if (ON(0)) {
;         constexpr int total = (D / 64) * (2 * FF / 32);
;         for (int it = gw; it < total; it += NGW) { int r = it; tj(a->w_gu1, D, 2 * FF, Wgu, 0, 2 * FF, 0, 2, r, scr, lane); }
;     }
.LBB0_27:
	s_cmpk_gt_i32 s30, 0x2bff
	v_lshrrev_b32_e32 v157, 3, v156
	v_lshlrev_b32_e32 v158, 3, v156
	s_cbranch_scc1 .LBB0_32
	s_sub_i32 s98, s34, 0x480
	s_mov_b32 s99, s30
	s_movk_i32 s100, 0x2c00
	s_cmp_gt_i32 s98, 0
	s_cbranch_scc1 .Lp0_split
	s_mov_b32 s98, s34
	s_branch .Lp0_go
.Lp0_split:
	s_cmpk_lt_i32 s30, 0x480
	s_cbranch_scc0 .Lp0_go
	s_movk_i32 s98, 0x480
	s_movk_i32 s100, 0x480

; #define LAS __attribute__((address_space(3)))
; __device__ __forceinline__ unsigned pk2(float lo, float hi) { return pg8::cvt_pk_bf16(lo, hi); }
; __device__ __forceinline__ void transpose_item(const float* W, int K, int N, bf16_t* WT, int dst0, int src0, int mode, int nblk, LAS float* scr, int item, int lane) {
;     const int kb = item / nblk, nb = item % nblk, k0 = 64 * kb, n0 = 32 * nb;
;     const int sc = srccol(mode, n0 + (lane & 31), src0);
; #pragma unroll 8
;     for (int i = 0; i < 32; ++i) { const int kk = 2 * i + (lane >> 5); scr[kk * 33 + (lane & 31)] = __builtin_nontemporal_load(W + (size_t)(k0 + kk) * N + sc); }
;     asm volatile("s_waitcnt lgkmcnt(0)" ::: "memory");
;     const int c = lane & 7;
; #pragma unroll
;     for (int j = 0; j < 4; ++j) { const int n = (lane >> 3) + 8 * j; const LAS float* s = scr + (8 * c) * 33 + n;
;         u32x4 o; o.x = pk2(s[0 * 33], s[1 * 33]); o.y = pk2(s[2 * 33], s[3 * 33]); o.z = pk2(s[4 * 33], s[5 * 33]); o.w = pk2(s[6 * 33], s[7 * 33]);
;         *(u32x4*)(WT + (size_t)(dst0 + n0 + n) * K + k0 + 8 * c) = o; }
;     asm volatile("s_waitcnt lgkmcnt(0)" ::: "memory");
; }
.LBB0_30:
	v_lshl_add_u64 v[34:35], v[16:17], 0, s[8:9]
	v_lshl_add_u64 v[36:37], v[14:15], 0, s[8:9]
	v_lshl_add_u64 v[38:39], v[12:13], 0, s[8:9]
	v_lshl_add_u64 v[40:41], v[10:11], 0, s[8:9]
	v_lshl_add_u64 v[42:43], v[8:9], 0, s[8:9]
	v_lshl_add_u64 v[44:45], v[6:7], 0, s[8:9]
	v_lshl_add_u64 v[46:47], v[4:5], 0, s[8:9]
	v_lshl_add_u64 v[48:49], v[2:3], 0, s[8:9]
	global_load_dword v104, v[34:35], off nt
	global_load_dword v105, v[36:37], off nt
	global_load_dword v106, v[38:39], off nt
	global_load_dword v107, v[40:41], off nt
	global_load_dword v108, v[42:43], off nt
	global_load_dword v109, v[44:45], off nt
	global_load_dword v110, v[46:47], off nt
	global_load_dword v111, v[48:49], off nt
	s_add_u32 s8, s8, 0xb0000
	s_addc_u32 s9, s9, 0
	v_lshl_add_u64 v[34:35], v[16:17], 0, s[8:9]
	v_lshl_add_u64 v[36:37], v[14:15], 0, s[8:9]
	v_lshl_add_u64 v[38:39], v[12:13], 0, s[8:9]
	v_lshl_add_u64 v[40:41], v[10:11], 0, s[8:9]
	v_lshl_add_u64 v[42:43], v[8:9], 0, s[8:9]
	v_lshl_add_u64 v[44:45], v[6:7], 0, s[8:9]
	v_lshl_add_u64 v[46:47], v[4:5], 0, s[8:9]
	v_lshl_add_u64 v[48:49], v[2:3], 0, s[8:9]
	global_load_dword v112, v[34:35], off nt
	global_load_dword v113, v[36:37], off nt
	global_load_dword v114, v[38:39], off nt
	global_load_dword v115, v[40:41], off nt
	global_load_dword v116, v[42:43], off nt
	global_load_dword v117, v[44:45], off nt
	global_load_dword v118, v[46:47], off nt
	global_load_dword v119, v[48:49], off nt
	s_add_u32 s8, s8, 0xb0000
	s_addc_u32 s9, s9, 0
	v_lshl_add_u64 v[34:35], v[16:17], 0, s[8:9]
	v_lshl_add_u64 v[36:37], v[14:15], 0, s[8:9]
	v_lshl_add_u64 v[38:39], v[12:13], 0, s[8:9]
	v_lshl_add_u64 v[40:41], v[10:11], 0, s[8:9]
	v_lshl_add_u64 v[42:43], v[8:9], 0, s[8:9]
	v_lshl_add_u64 v[44:45], v[6:7], 0, s[8:9]
	v_lshl_add_u64 v[46:47], v[4:5], 0, s[8:9]
	v_lshl_add_u64 v[48:49], v[2:3], 0, s[8:9]
	global_load_dword v120, v[34:35], off nt
	global_load_dword v121, v[36:37], off nt
	global_load_dword v122, v[38:39], off nt
	global_load_dword v123, v[40:41], off nt
	global_load_dword v124, v[42:43], off nt
	global_load_dword v125, v[44:45], off nt
	global_load_dword v126, v[46:47], off nt
	global_load_dword v127, v[48:49], off nt
	s_add_u32 s8, s8, 0xb0000
	s_addc_u32 s9, s9, 0
	v_lshl_add_u64 v[34:35], v[16:17], 0, s[8:9]
	v_lshl_add_u64 v[36:37], v[14:15], 0, s[8:9]
	v_lshl_add_u64 v[38:39], v[12:13], 0, s[8:9]
	v_lshl_add_u64 v[40:41], v[10:11], 0, s[8:9]
	v_lshl_add_u64 v[42:43], v[8:9], 0, s[8:9]
	v_lshl_add_u64 v[44:45], v[6:7], 0, s[8:9]
	v_lshl_add_u64 v[46:47], v[4:5], 0, s[8:9]
	v_lshl_add_u64 v[48:49], v[2:3], 0, s[8:9]
	global_load_dword v128, v[34:35], off nt
	global_load_dword v129, v[36:37], off nt
	global_load_dword v130, v[38:39], off nt
	global_load_dword v131, v[40:41], off nt
	global_load_dword v132, v[42:43], off nt
	global_load_dword v133, v[44:45], off nt
	global_load_dword v134, v[46:47], off nt
	global_load_dword v135, v[48:49], off nt
	s_add_u32 s8, s8, 0xb0000
	s_addc_u32 s9, s9, 0
	v_add_u32_e32 v34, 0x400, v32
	s_waitcnt vmcnt(30)
	ds_write2_b32 v32, v104, v105 offset1:66
	s_waitcnt vmcnt(28)
	ds_write2_b32 v32, v106, v107 offset0:132 offset1:198
	s_waitcnt vmcnt(26)
	ds_write2_b32 v34, v108, v109 offset0:8 offset1:74
	s_waitcnt vmcnt(24)
	ds_write2_b32 v34, v110, v111 offset0:140 offset1:206
	v_add_u32_e32 v32, 0x840, v32
	v_add_u32_e32 v34, 0x400, v32
	s_waitcnt vmcnt(22)
	ds_write2_b32 v32, v112, v113 offset1:66
	s_waitcnt vmcnt(20)
	ds_write2_b32 v32, v114, v115 offset0:132 offset1:198
	s_waitcnt vmcnt(18)
	ds_write2_b32 v34, v116, v117 offset0:8 offset1:74
	s_waitcnt vmcnt(16)
	ds_write2_b32 v34, v118, v119 offset0:140 offset1:206
	v_add_u32_e32 v32, 0x840, v32
	v_add_u32_e32 v34, 0x400, v32
	s_waitcnt vmcnt(14)
	ds_write2_b32 v32, v120, v121 offset1:66
	s_waitcnt vmcnt(12)
	ds_write2_b32 v32, v122, v123 offset0:132 offset1:198
	s_waitcnt vmcnt(10)
	ds_write2_b32 v34, v124, v125 offset0:8 offset1:74
	s_waitcnt vmcnt(8)
	ds_write2_b32 v34, v126, v127 offset0:140 offset1:206
	v_add_u32_e32 v32, 0x840, v32
	v_add_u32_e32 v34, 0x400, v32
	s_waitcnt vmcnt(6)
	ds_write2_b32 v32, v128, v129 offset1:66
	s_waitcnt vmcnt(4)
	ds_write2_b32 v32, v130, v131 offset0:132 offset1:198
	s_waitcnt vmcnt(2)
	ds_write2_b32 v34, v132, v133 offset0:8 offset1:74
	s_waitcnt vmcnt(0)
	ds_write2_b32 v34, v134, v135 offset0:140 offset1:206
	v_add_u32_e32 v32, 0x840, v32
	s_cmp_lg_u32 s8, 0x2c0000
	s_waitcnt lgkmcnt(0)
	ds_read2_b32 v[6:7], v20 offset0:33 offset1:41
	ds_read2_b32 v[8:9], v20 offset1:8
	ds_read2_b32 v[10:11], v20 offset0:66 offset1:74
	ds_read2_b32 v[12:13], v20 offset0:99 offset1:107
	ds_read2_b32 v[14:15], v20 offset0:132 offset1:140
	ds_read2_b32 v[16:17], v20 offset0:165 offset1:173
	ds_read2_b32 v[32:33], v20 offset0:198 offset1:206
	ds_read2_b32 v[34:35], v20 offset0:231 offset1:239
	v_or_b32_e32 v38, s12, v157
	s_ashr_i32 s5, s4, 31
	v_ashrrev_i32_e32 v39, 31, v38
	v_lshl_add_u64 v[36:37], s[4:5], 1, v[0:1]
	v_lshlrev_b64 v[38:39], 12, v[38:39]
	s_waitcnt lgkmcnt(6)
	v_cvt_pk_bf16_f32 v2, v8, v6
	s_waitcnt lgkmcnt(4)
	v_cvt_pk_bf16_f32 v3, v10, v12
	s_waitcnt lgkmcnt(2)
	v_cvt_pk_bf16_f32 v4, v14, v16
	s_waitcnt lgkmcnt(0)
	v_cvt_pk_bf16_f32 v5, v32, v34
	v_lshl_add_u64 v[38:39], v[36:37], 0, v[38:39]
	v_or_b32_e32 v6, s12, v21
	global_store_dwordx4 v[38:39], v[2:5], off
	s_add_i32 s11, s11, s98
	s_cmp_ge_i32 s11, s100
	v_cvt_pk_bf16_f32 v2, v9, v7
	v_ashrrev_i32_e32 v7, 31, v6
	v_cvt_pk_bf16_f32 v3, v11, v13
	v_cvt_pk_bf16_f32 v4, v15, v17
	v_cvt_pk_bf16_f32 v5, v33, v35
	v_lshlrev_b64 v[6:7], 12, v[6:7]
	ds_read2_b32 v[8:9], v20 offset0:49 offset1:57
	ds_read2_b32 v[10:11], v20 offset0:16 offset1:24
	ds_read2_b32 v[12:13], v20 offset0:82 offset1:90
	ds_read2_b32 v[14:15], v20 offset0:115 offset1:123
	ds_read2_b32 v[16:17], v20 offset0:148 offset1:156
	ds_read2_b32 v[32:33], v20 offset0:181 offset1:189
	ds_read2_b32 v[34:35], v20 offset0:214 offset1:222
	ds_read2_b32 v[38:39], v20 offset0:247 offset1:255
	v_lshl_add_u64 v[6:7], v[36:37], 0, v[6:7]
	global_store_dwordx4 v[6:7], v[2:5], off
	v_or_b32_e32 v6, s12, v22
	v_ashrrev_i32_e32 v7, 31, v6
	v_lshlrev_b64 v[6:7], 12, v[6:7]
	s_waitcnt lgkmcnt(6)
	v_cvt_pk_bf16_f32 v2, v10, v8
	s_waitcnt lgkmcnt(4)
	v_cvt_pk_bf16_f32 v3, v12, v14
	s_waitcnt lgkmcnt(2)
	v_cvt_pk_bf16_f32 v4, v16, v32
	s_waitcnt lgkmcnt(0)
	v_cvt_pk_bf16_f32 v5, v34, v38
	v_lshl_add_u64 v[6:7], v[36:37], 0, v[6:7]
	global_store_dwordx4 v[6:7], v[2:5], off
	v_or_b32_e32 v6, s12, v23
	v_ashrrev_i32_e32 v7, 31, v6
	v_lshlrev_b64 v[6:7], 12, v[6:7]
	v_cvt_pk_bf16_f32 v2, v11, v9
	v_cvt_pk_bf16_f32 v3, v13, v15
	v_cvt_pk_bf16_f32 v4, v17, v33
	v_cvt_pk_bf16_f32 v5, v35, v39
	v_lshl_add_u64 v[6:7], v[36:37], 0, v[6:7]
	global_store_dwordx4 v[6:7], v[2:5], off
	s_waitcnt lgkmcnt(0)
	s_cbranch_scc0 .LBB0_29
